# v22 + QKV rope-load hoist + mLSTM waves 6,7 output epilogue deferred past the chunk barrier
# baseline (speedup 1.0000x reference)
; DI unsigned pk2(float lo, float hi) { f32x2 v = {lo, hi}; bf16x2_t b = __builtin_convertvector(v, bf16x2_t); return __builtin_bit_cast(unsigned, b); }
; DI void mlstm_phase(LAS unsigned char* lds, const bf16_t* proj, const float* gates, bf16_t* Hfw, bf16_t* Hbw, int G, int bid) {
;     ...
;                 const float dn = __shfl(nacc[4][0], fr);
;                 const float dd = fmaxf(fabsf(dn), __expf(-(bt + Mt)));
;                 const float inv = 1.0f / dd;
;                 bf16_t* op = Hout + MTOK(c * 128 + t) * D + hh * 256 + sl * 64 + 4 * fq;
;                 u32x2 w[4];
; #pragma unroll
;                 for (int dt = 0; dt < 4; ++dt) { w[dt].x = pk2(nacc[dt][0] * inv, nacc[dt][1] * inv); w[dt].y = pk2(nacc[dt][2] * inv, nacc[dt][3] * inv); }
;                 { const bool odd = (fq & 1) != 0;
;                   const u32x2 s01 = odd ? w[0] : w[1], s23 = odd ? w[2] : w[3];
;                   u32x2 r01, r23; r01.x = __shfl_xor(s01.x, 16); r01.y = __shfl_xor(s01.y, 16); r23.x = __shfl_xor(s23.x, 16); r23.y = __shfl_xor(s23.y, 16);
;                   const u32x4 o0 = odd ? (u32x4){r01.x, r01.y, w[1].x, w[1].y} : (u32x4){w[0].x, w[0].y, r01.x, r01.y};
;                   const u32x4 o1 = odd ? (u32x4){r23.x, r23.y, w[3].x, w[3].y} : (u32x4){w[2].x, w[2].y, r23.x, r23.y};
;                   bf16_t* ob = op - 4 * fq + 8 * (fq >> 1) + (odd ? 16 : 0);
;                   __builtin_nontemporal_store(o0, (u32x4*)ob); __builtin_nontemporal_store(o1, (u32x4*)(ob + 32)); }
;             }
;             if (nown > 0) {
;                 const float decay = __expf(mp - M127);
; #pragma unroll
.LBB0_851:
	s_andn2_b64 vcc, exec, s[6:7]
	s_cbranch_vccnz .Lmepi_skip
	v_and_b32_e32 v0, 64, v193
	v_add_f32_e32 v2, v2, v3
	v_mul_f32_e32 v2, 0xbfb8aa3b, v2
	v_exp_f32_e32 v2, v2
	s_nop 4
	v_max_f32_e64 v3, |v104|, |v104|
	v_max_f32_e32 v2, v3, v2
	v_div_scale_f32 v3, s[92:93], v2, v2, 1.0
	v_rcp_f32_e32 v100, v3
	v_div_scale_f32 v101, vcc, 1.0, v2, 1.0
	v_fma_f32 v102, -v3, v100, 1.0
	v_fmac_f32_e32 v100, v102, v100
	v_mul_f32_e32 v102, v101, v100
	v_fma_f32 v103, -v3, v102, v101
	v_fmac_f32_e32 v102, v103, v100
	v_fma_f32 v3, -v3, v102, v101
	v_div_fmas_f32 v3, v3, v100, v102
	v_div_fixup_f32 v2, v3, v2, 1.0
	v_add_u32_e32 v3, s48, v150
	v_pk_mul_f32 v[84:85], v[84:85], v[2:3] op_sel_hi:[1,0]
	v_add_u32_e32 v100, s46, v178
	v_cvt_pk_bf16_f32 v102, v84, v85
	v_pk_mul_f32 v[84:85], v[86:87], v[2:3] op_sel_hi:[1,0]
	v_cndmask_b32_e64 v100, v100, v3, s[90:91]
	v_cvt_pk_bf16_f32 v103, v84, v85
	v_pk_mul_f32 v[84:85], v[88:89], v[2:3] op_sel_hi:[1,0]
	v_ashrrev_i32_e32 v101, 31, v100
	v_cvt_pk_bf16_f32 v86, v84, v85
	v_pk_mul_f32 v[84:85], v[90:91], v[2:3] op_sel_hi:[1,0]
	v_lshl_add_u64 v[100:101], v[100:101], 0, s[96:97]
	v_cvt_pk_bf16_f32 v87, v84, v85
	v_pk_mul_f32 v[84:85], v[92:93], v[2:3] op_sel_hi:[1,0]
	v_xor_b32_e32 v93, 16, v193
	v_cvt_pk_bf16_f32 v88, v84, v85
	v_pk_mul_f32 v[84:85], v[94:95], v[2:3] op_sel_hi:[1,0]
	v_add_u32_e32 v94, 64, v0
	v_cmp_lt_i32_e32 vcc, v93, v94
	v_cvt_pk_bf16_f32 v89, v84, v85
	v_pk_mul_f32 v[84:85], v[96:97], v[2:3] op_sel_hi:[1,0]
	v_pk_mul_f32 v[2:3], v[98:99], v[2:3] op_sel_hi:[1,0]
	v_cndmask_b32_e32 v93, v193, v93, vcc
	v_cvt_pk_bf16_f32 v90, v84, v85
	v_cvt_pk_bf16_f32 v91, v2, v3
	v_cndmask_b32_e64 v84, v103, v87, s[12:13]
	v_cndmask_b32_e64 v85, v102, v86, s[12:13]
	v_lshlrev_b32_e32 v93, 2, v93
	v_cndmask_b32_e64 v92, v89, v91, s[12:13]
	ds_bpermute_b32 v84, v93, v84
	ds_bpermute_b32 v94, v93, v85
	v_cndmask_b32_e64 v85, v88, v90, s[12:13]
	ds_bpermute_b32 v95, v93, v85
	ds_bpermute_b32 v92, v93, v92
	v_lshlrev_b64 v[2:3], 11, v[100:101]
	s_waitcnt lgkmcnt(3)
	v_cndmask_b32_e64 v87, v87, v84, s[12:13]
	s_waitcnt lgkmcnt(2)
	v_cndmask_b32_e64 v86, v86, v94, s[12:13]
	v_cndmask_b32_e64 v85, v84, v103, s[12:13]
	v_cndmask_b32_e64 v84, v94, v102, s[12:13]
	v_lshl_add_u64 v[2:3], v[136:137], 0, v[2:3]
	s_waitcnt lgkmcnt(0)
	v_cndmask_b32_e64 v91, v91, v92, s[12:13]
	v_cndmask_b32_e64 v90, v90, v95, s[12:13]
	v_cndmask_b32_e64 v89, v92, v89, s[12:13]
	v_cndmask_b32_e64 v88, v95, v88, s[12:13]
	global_store_dwordx4 v[2:3], v[84:87], off nt
	global_store_dwordx4 v[2:3], v[88:91], off offset:64 nt
.Lmepi_skip:
	v_cndmask_b32_e64 v0, 0, 1, s[6:7]
	v_cmp_ne_u32_e64 s[94:95], 1, v0
	v_cndmask_b32_e64 v0, 0, 1, s[4:5]
	s_andn2_b64 vcc, exec, s[6:7]
	v_cmp_ne_u32_e64 s[92:93], 1, v0
	s_cbranch_vccnz .LBB0_869
	v_add_u32_e32 v2, v165, v152
	ds_read_b64_tr_b16 v[84:85], v2 offset:34816
	v_add_u32_e32 v2, v166, v152
	ds_read_b64_tr_b16 v[86:87], v2 offset:34816
	s_and_b64 vcc, exec, s[92:93]
	s_waitcnt lgkmcnt(1)
	v_mov_b32_e32 v88, v84
	v_mov_b32_e32 v89, v85
	s_waitcnt lgkmcnt(0)
	v_mov_b32_e32 v90, v86
	v_mov_b32_e32 v91, v87
	s_cbranch_vccnz .LBB0_854
	v_add_u32_e32 v2, v165, v154
	v_add_u32_e32 v3, v166, v154
	ds_read_b64_tr_b16 v[88:89], v2 offset:34816
	ds_read_b64_tr_b16 v[90:91], v3 offset:34816

; #define LAS __attribute__((address_space(3)))
; DI unsigned pk2(float lo, float hi) { f32x2 v = {lo, hi}; bf16x2_t b = __builtin_convertvector(v, bf16x2_t); return __builtin_bit_cast(unsigned, b); }
; DI void mlstm_phase(LAS unsigned char* lds, const bf16_t* proj, const float* gates, bf16_t* Hfw, bf16_t* Hbw, int G, int bid) {
;     ...
;                 const float dn = __shfl(nacc[4][0], fr);
;                 const float dd = fmaxf(fabsf(dn), __expf(-(bt + Mt)));
;                 const float inv = 1.0f / dd;
;                 bf16_t* op = Hout + MTOK(c * 128 + t) * D + hh * 256 + sl * 64 + 4 * fq;
;                 u32x2 w[4];
; #pragma unroll
;                 for (int dt = 0; dt < 4; ++dt) { w[dt].x = pk2(nacc[dt][0] * inv, nacc[dt][1] * inv); w[dt].y = pk2(nacc[dt][2] * inv, nacc[dt][3] * inv); }
;                 { const bool odd = (fq & 1) != 0;
;                   const u32x2 s01 = odd ? w[0] : w[1], s23 = odd ? w[2] : w[3];
;                   u32x2 r01, r23; r01.x = __shfl_xor(s01.x, 16); r01.y = __shfl_xor(s01.y, 16); r23.x = __shfl_xor(s23.x, 16); r23.y = __shfl_xor(s23.y, 16);
;                   const u32x4 o0 = odd ? (u32x4){r01.x, r01.y, w[1].x, w[1].y} : (u32x4){w[0].x, w[0].y, r01.x, r01.y};
;                   const u32x4 o1 = odd ? (u32x4){r23.x, r23.y, w[3].x, w[3].y} : (u32x4){w[2].x, w[2].y, r23.x, r23.y};
;                   bf16_t* ob = op - 4 * fq + 8 * (fq >> 1) + (odd ? 16 : 0);
;                   __builtin_nontemporal_store(o0, (u32x4*)ob); __builtin_nontemporal_store(o1, (u32x4*)(ob + 32)); }
;     ...
;             if (wid == 2 && c + 1 < nc) GATES(cur ^ 1);
;             LBAR();
;             if (nown > 0) {
; #pragma unroll
;                 for (int dt = 0; dt < 5; ++dt)
; #pragma unroll
;                     for (int i = 0; i < 4; ++i)
;                         *(LAS bf16_t*)(Cs + (16 * dt + 4 * fq + i) * MQ_STRIDE + (16 * wid + fr) * 2) = (bf16_t)(pk2(Creg[0][dt][i], 0.f) & 0xffffu);
;                 if (nown == 2) {
; #pragma unroll
;                     for (int dt = 0; dt < 5; ++dt)
; #pragma unroll
;                         for (int i = 0; i < 4; ++i)
;                             *(LAS bf16_t*)(Cs + (16 * dt + 4 * fq + i) * MQ_STRIDE + (16 * (wid + 6) + fr) * 2) = (bf16_t)(pk2(Creg[1][dt][i], 0.f) & 0xffffu);
;                 }
;             }
.LBB0_873:
	s_waitcnt lgkmcnt(0)
	s_barrier
	s_andn2_b64 vcc, exec, s[6:7]
	s_cbranch_vccz .Lmepi_after
	v_and_b32_e32 v0, 64, v193
	v_add_f32_e32 v2, v2, v3
	v_mul_f32_e32 v2, 0xbfb8aa3b, v2
	v_exp_f32_e32 v2, v2
	s_nop 4
	v_max_f32_e64 v3, |v104|, |v104|
	v_max_f32_e32 v2, v3, v2
	v_div_scale_f32 v3, s[92:93], v2, v2, 1.0
	v_rcp_f32_e32 v100, v3
	v_div_scale_f32 v101, vcc, 1.0, v2, 1.0
	v_fma_f32 v102, -v3, v100, 1.0
	v_fmac_f32_e32 v100, v102, v100
	v_mul_f32_e32 v102, v101, v100
	v_fma_f32 v103, -v3, v102, v101
	v_fmac_f32_e32 v102, v103, v100
	v_fma_f32 v3, -v3, v102, v101
	v_div_fmas_f32 v3, v3, v100, v102
	v_div_fixup_f32 v2, v3, v2, 1.0
	v_add_u32_e32 v3, s48, v150
	v_pk_mul_f32 v[84:85], v[84:85], v[2:3] op_sel_hi:[1,0]
	v_add_u32_e32 v100, s46, v178
	v_cvt_pk_bf16_f32 v102, v84, v85
	v_pk_mul_f32 v[84:85], v[86:87], v[2:3] op_sel_hi:[1,0]
	v_cndmask_b32_e64 v100, v100, v3, s[90:91]
	v_cvt_pk_bf16_f32 v103, v84, v85
	v_pk_mul_f32 v[84:85], v[88:89], v[2:3] op_sel_hi:[1,0]
	v_ashrrev_i32_e32 v101, 31, v100
	v_cvt_pk_bf16_f32 v86, v84, v85
	v_pk_mul_f32 v[84:85], v[90:91], v[2:3] op_sel_hi:[1,0]
	v_lshl_add_u64 v[100:101], v[100:101], 0, s[96:97]
	v_cvt_pk_bf16_f32 v87, v84, v85
	v_pk_mul_f32 v[84:85], v[92:93], v[2:3] op_sel_hi:[1,0]
	v_xor_b32_e32 v93, 16, v193
	v_cvt_pk_bf16_f32 v88, v84, v85
	v_pk_mul_f32 v[84:85], v[94:95], v[2:3] op_sel_hi:[1,0]
	v_add_u32_e32 v94, 64, v0
	v_cmp_lt_i32_e32 vcc, v93, v94
	v_cvt_pk_bf16_f32 v89, v84, v85
	v_pk_mul_f32 v[84:85], v[96:97], v[2:3] op_sel_hi:[1,0]
	v_pk_mul_f32 v[2:3], v[98:99], v[2:3] op_sel_hi:[1,0]
	v_cndmask_b32_e32 v93, v193, v93, vcc
	v_cvt_pk_bf16_f32 v90, v84, v85
	v_cvt_pk_bf16_f32 v91, v2, v3
	v_cndmask_b32_e64 v84, v103, v87, s[12:13]
	v_cndmask_b32_e64 v85, v102, v86, s[12:13]
	v_lshlrev_b32_e32 v93, 2, v93
	v_cndmask_b32_e64 v92, v89, v91, s[12:13]
	ds_bpermute_b32 v84, v93, v84
	ds_bpermute_b32 v94, v93, v85
	v_cndmask_b32_e64 v85, v88, v90, s[12:13]
	ds_bpermute_b32 v95, v93, v85
	ds_bpermute_b32 v92, v93, v92
	v_lshlrev_b64 v[2:3], 11, v[100:101]
	s_waitcnt lgkmcnt(3)
	v_cndmask_b32_e64 v87, v87, v84, s[12:13]
	s_waitcnt lgkmcnt(2)
	v_cndmask_b32_e64 v86, v86, v94, s[12:13]
	v_cndmask_b32_e64 v85, v84, v103, s[12:13]
	v_cndmask_b32_e64 v84, v94, v102, s[12:13]
	v_lshl_add_u64 v[2:3], v[136:137], 0, v[2:3]
	s_waitcnt lgkmcnt(0)
	v_cndmask_b32_e64 v91, v91, v92, s[12:13]
	v_cndmask_b32_e64 v90, v90, v95, s[12:13]
	v_cndmask_b32_e64 v89, v92, v89, s[12:13]
	v_cndmask_b32_e64 v88, v95, v88, s[12:13]
	global_store_dwordx4 v[2:3], v[84:87], off nt
	global_store_dwordx4 v[2:3], v[88:91], off offset:64 nt
.Lmepi_after:
	s_and_b64 vcc, exec, s[94:95]
	s_cbranch_vccnz .LBB0_835
	v_cvt_pk_bf16_f32 v0, v80, s0
	ds_write_b16 v199, v0
	v_cvt_pk_bf16_f32 v0, v81, s0
	ds_write_b16 v199, v0 offset:272
	v_cvt_pk_bf16_f32 v0, v82, s0
	ds_write_b16 v199, v0 offset:544
	v_cvt_pk_bf16_f32 v0, v83, s0
	ds_write_b16 v199, v0 offset:816
	v_cvt_pk_bf16_f32 v0, v76, s0
	ds_write_b16 v199, v0 offset:4352
	v_cvt_pk_bf16_f32 v0, v77, s0
	ds_write_b16 v199, v0 offset:4624
	v_cvt_pk_bf16_f32 v0, v78, s0
	ds_write_b16 v199, v0 offset:4896
	v_cvt_pk_bf16_f32 v0, v79, s0
	ds_write_b16 v199, v0 offset:5168
	v_cvt_pk_bf16_f32 v0, v72, s0
	ds_write_b16 v199, v0 offset:8704
	v_cvt_pk_bf16_f32 v0, v73, s0
	ds_write_b16 v199, v0 offset:8976
	v_cvt_pk_bf16_f32 v0, v74, s0
	ds_write_b16 v199, v0 offset:9248
	v_cvt_pk_bf16_f32 v0, v75, s0
	ds_write_b16 v199, v0 offset:9520
	v_cvt_pk_bf16_f32 v0, v68, s0
	ds_write_b16 v199, v0 offset:13056
	v_cvt_pk_bf16_f32 v0, v69, s0
	ds_write_b16 v199, v0 offset:13328
	v_cvt_pk_bf16_f32 v0, v70, s0
	ds_write_b16 v199, v0 offset:13600
	v_cvt_pk_bf16_f32 v0, v71, s0
	ds_write_b16 v199, v0 offset:13872
	v_cvt_pk_bf16_f32 v0, v64, s0
	ds_write_b16 v199, v0 offset:17408
	v_cvt_pk_bf16_f32 v0, v65, s0
	ds_write_b16 v199, v0 offset:17680
	v_cvt_pk_bf16_f32 v0, v66, s0
	ds_write_b16 v199, v0 offset:17952
	v_cvt_pk_bf16_f32 v0, v67, s0
	s_and_b64 vcc, exec, s[92:93]
	ds_write_b16 v199, v0 offset:18224
	s_cbranch_vccnz .LBB0_835
	v_cvt_pk_bf16_f32 v0, v44, s0
	ds_write_b16 v200, v0
	v_cvt_pk_bf16_f32 v0, v45, s0
	ds_write_b16 v200, v0 offset:272
	v_cvt_pk_bf16_f32 v0, v46, s0
	ds_write_b16 v200, v0 offset:544
	v_cvt_pk_bf16_f32 v0, v47, s0
	ds_write_b16 v200, v0 offset:816
	v_cvt_pk_bf16_f32 v0, v48, s0
	ds_write_b16 v200, v0 offset:4352
	v_cvt_pk_bf16_f32 v0, v49, s0
	ds_write_b16 v200, v0 offset:4624
	v_cvt_pk_bf16_f32 v0, v50, s0
	ds_write_b16 v200, v0 offset:4896
	v_cvt_pk_bf16_f32 v0, v51, s0
	ds_write_b16 v200, v0 offset:5168
	v_cvt_pk_bf16_f32 v0, v52, s0
	ds_write_b16 v200, v0 offset:8704
	v_cvt_pk_bf16_f32 v0, v53, s0
	ds_write_b16 v200, v0 offset:8976
	v_cvt_pk_bf16_f32 v0, v54, s0
	ds_write_b16 v200, v0 offset:9248
	v_cvt_pk_bf16_f32 v0, v55, s0
	ds_write_b16 v200, v0 offset:9520
	v_cvt_pk_bf16_f32 v0, v56, s0
	ds_write_b16 v200, v0 offset:13056
	v_cvt_pk_bf16_f32 v0, v57, s0
	ds_write_b16 v200, v0 offset:13328
	v_cvt_pk_bf16_f32 v0, v58, s0
	ds_write_b16 v200, v0 offset:13600
	v_cvt_pk_bf16_f32 v0, v59, s0
	ds_write_b16 v200, v0 offset:13872
	v_cvt_pk_bf16_f32 v0, v60, s0
	ds_write_b16 v200, v0 offset:17408
	v_cvt_pk_bf16_f32 v0, v61, s0
	ds_write_b16 v200, v0 offset:17680
	v_cvt_pk_bf16_f32 v0, v62, s0
	ds_write_b16 v200, v0 offset:17952
	v_cvt_pk_bf16_f32 v0, v63, s0
	ds_write_b16 v200, v0 offset:18224
	s_branch .LBB0_835
